# selected and sliding-window interior tiles: K fragment reads up front, V fragment reads behind the last QK MFMA (v212-v243)
# baseline (speedup 1.0000x reference)
; #define LAS __attribute__((address_space(3)))
; template <int BR>
; DI void attn_branch(const AttnCtx& c, unsigned long long tmask, const bf16_t* kbase, size_t kpitch, const bf16_t* vbase, size_t vpitch, f32x16 (&o)[2], float& lsum) {
;     ...
;         bool mine = true;
;         if (BR == 2) mine = (c.mymask >> jc) & 1ull;
;         const bool wave_on = (BR == 2 ? (__ballot(mine) != 0ull) : true) && !c.nocompute;
;         if (wave_on) {
;             const float sbias = (BR == 2 && !mine) ? -1e30f : 0.f;
;             bool interior;
;             if (BR <= 1) interior = jc * 64 + 64 <= c.ncvmin;
;             else if (BR == 2) interior = jc * 64 + 63 <= c.tw;
;             else interior = (jc * 64 + 63 <= c.tw) && (jc * 64 > c.tw + 31 - 512);
;             if (interior) {
;                 f32x16 s0, s1;
; #pragma unroll
;                 for (int i = 0; i < 16; ++i) { s0[i] = sbias; s1[i] = sbias; }
; #pragma unroll
;                 for (int st = 0; st < 4; ++st) {
;                     const bf16x8 kf0 = *(const LAS bf16x8*)(Ks + c.qi * 72 + 16 * st + 8 * c.hi), kf1 = *(const LAS bf16x8*)(Ks + (32 + c.qi) * 72 + 16 * st + 8 * c.hi);
;                     s0 = MFMA32(kf0, c.q[st], s0); s1 = MFMA32(kf1, c.q[st], s1);
;                 }
;                 float p0[16], p1[16];
; #pragma unroll
;                 for (int i = 0; i < 16; ++i) { p0[i] = __builtin_amdgcn_exp2f(s0[i]); p1[i] = __builtin_amdgcn_exp2f(s1[i]); }
;                 {
;                     float l0 = 0.f, l1 = 0.f;
; #pragma unroll
;                     for (int i = 0; i < 16; ++i) { l0 += p0[i]; l1 += p1[i]; }
;                     lsum += l0 + l1;
;                 }
;                 if (BR == 1) {
; #pragma unroll
;                     for (int gq = 0; gq < 4; ++gq) {
;                         const int jj = jc * 16 + gq * 2 + c.hi;
;                         __hip_atomic_fetch_add(c.impw + jj, (p0[4 * gq] + p0[4 * gq + 1]) + (p0[4 * gq + 2] + p0[4 * gq + 3]), __ATOMIC_RELAXED, __HIP_MEMORY_SCOPE_WORKGROUP);
;                         __hip_atomic_fetch_add(c.impw + jj + 1, p0[4 * gq + 3], __ATOMIC_RELAXED, __HIP_MEMORY_SCOPE_WORKGROUP);
;                     }
; #pragma unroll
;                     for (int gq = 0; gq < 4; ++gq) {
;                         const int jj = jc * 16 + 8 + gq * 2 + c.hi;
.LBB0_377:
	s_waitcnt lgkmcnt(0)
	s_barrier
	v_lshrrev_b64 v[64:65], s10, v[106:107]
	v_and_b32_e32 v64, 1, v64
	v_cmp_eq_u32_e64 s[0:1], 1, v64
	v_cmp_ne_u32_e32 vcc, 0, v64
	s_cbranch_vccz .LBB0_387
	s_lshl_b32 s15, s10, 6
	v_cndmask_b32_e64 v64, v193, 0, s[0:1]
	s_or_b32 s0, s15, 63
	v_cmp_le_i32_e32 vcc, s0, v171
	s_and_saveexec_b64 s[0:1], vcc
	s_xor_b64 s[0:1], exec, s[0:1]
	s_cbranch_execz .LBB0_380
	v_lshlrev_b32_e32 v80, 1, v170
	v_add3_u32 v109, s14, v185, v80
	ds_read_b128 v[212:215], v109
	ds_read_b128 v[216:219], v109 offset:4608
	ds_read_b128 v[220:223], v109 offset:32
	ds_read_b128 v[224:227], v109 offset:4640
	ds_read_b128 v[228:231], v109 offset:64
	ds_read_b128 v[232:235], v109 offset:4672
	ds_read_b128 v[236:239], v109 offset:96
	ds_read_b128 v[240:243], v109 offset:4704
	v_mov_b32_e32 v65, v64
	v_mov_b32_e32 v66, v64
	v_mov_b32_e32 v67, v64
	v_mov_b32_e32 v68, v64
	v_mov_b32_e32 v69, v64
	v_mov_b32_e32 v70, v64
	v_mov_b32_e32 v71, v64
	v_mov_b32_e32 v72, v64
	v_mov_b32_e32 v73, v64
	v_mov_b32_e32 v74, v64
	v_mov_b32_e32 v75, v64
	v_mov_b32_e32 v76, v64
	v_mov_b32_e32 v77, v64
	v_mov_b32_e32 v78, v64
	v_mov_b32_e32 v79, v64
	s_nop 0
	s_waitcnt lgkmcnt(7)
	v_mfma_f32_32x32x16_bf16 v[80:95], v[212:215], v[130:133], v[64:79]
	s_waitcnt lgkmcnt(6)
	v_mfma_f32_32x32x16_bf16 v[64:79], v[216:219], v[130:133], v[64:79]
	s_waitcnt lgkmcnt(5)
	v_mfma_f32_32x32x16_bf16 v[80:95], v[220:223], v[134:137], v[80:95]
	s_waitcnt lgkmcnt(4)
	v_mfma_f32_32x32x16_bf16 v[64:79], v[224:227], v[134:137], v[64:79]
	s_waitcnt lgkmcnt(3)
	v_mfma_f32_32x32x16_bf16 v[80:95], v[228:231], v[138:141], v[80:95]
	s_waitcnt lgkmcnt(2)
	v_mfma_f32_32x32x16_bf16 v[64:79], v[232:235], v[138:141], v[64:79]
	s_waitcnt lgkmcnt(1)
	v_mfma_f32_32x32x16_bf16 v[80:95], v[236:239], v[142:145], v[80:95]
	s_waitcnt lgkmcnt(0)
	v_mfma_f32_32x32x16_bf16 v[64:79], v[240:243], v[142:145], v[64:79]
	v_add3_u32 v251, s14, v186, v170
	v_add_u32_e32 v255, 0x2000, v251
	v_add_u32_e32 v251, 0x3000, v251
	ds_read2_b64 v[212:215], v255 offset0:128 offset1:130
	ds_read2_b64 v[216:219], v255 offset0:136 offset1:138
	ds_read2_b64 v[220:223], v251 offset0:160 offset1:162
	ds_read2_b64 v[224:227], v251 offset0:168 offset1:170
	ds_read2_b64 v[228:231], v255 offset0:132 offset1:134
	ds_read2_b64 v[232:235], v255 offset0:140 offset1:142
	ds_read2_b64 v[236:239], v251 offset0:164 offset1:166
	ds_read2_b64 v[240:243], v251 offset0:172 offset1:174
	s_nop 9
	v_exp_f32_e32 v116, v80
	v_exp_f32_e32 v80, v82
	v_exp_f32_e32 v82, v84
	v_exp_f32_e32 v84, v86
	v_exp_f32_e32 v86, v88
	v_exp_f32_e32 v88, v89
	v_exp_f32_e32 v118, v90
	v_exp_f32_e32 v117, v64
	v_exp_f32_e32 v64, v81
	v_exp_f32_e32 v65, v65
	v_exp_f32_e32 v81, v66
	v_exp_f32_e32 v66, v83
	v_exp_f32_e32 v67, v67
	v_exp_f32_e32 v83, v68
	v_exp_f32_e32 v68, v85
	v_exp_f32_e32 v85, v70
	v_exp_f32_e32 v70, v87
	v_exp_f32_e32 v87, v72
	v_exp_f32_e32 v89, v73
	v_pk_add_f32 v[72:73], v[116:117], 0 op_sel_hi:[1,0]
	v_exp_f32_e32 v69, v69
	v_pk_add_f32 v[72:73], v[64:65], v[72:73]
	v_exp_f32_e32 v71, v71
	v_pk_add_f32 v[72:73], v[80:81], v[72:73]
	v_exp_f32_e32 v119, v74
	v_pk_add_f32 v[72:73], v[66:67], v[72:73]
	v_exp_f32_e32 v90, v91
	v_pk_add_f32 v[72:73], v[82:83], v[72:73]
	v_exp_f32_e32 v91, v75
	v_pk_add_f32 v[72:73], v[68:69], v[72:73]
	v_exp_f32_e32 v120, v92
	v_pk_add_f32 v[72:73], v[84:85], v[72:73]
	v_exp_f32_e32 v121, v76
	v_pk_add_f32 v[72:73], v[70:71], v[72:73]
	v_exp_f32_e32 v92, v93
	v_pk_add_f32 v[72:73], v[86:87], v[72:73]
	v_exp_f32_e32 v93, v77
	v_pk_add_f32 v[72:73], v[88:89], v[72:73]
	v_exp_f32_e32 v122, v94
	v_exp_f32_e32 v123, v78
	v_pk_add_f32 v[72:73], v[118:119], v[72:73]
	v_exp_f32_e32 v94, v95
	v_exp_f32_e32 v95, v79
	v_pk_add_f32 v[72:73], v[90:91], v[72:73]
	v_cvt_pk_bf16_f32 v79, v84, v70
	v_pk_add_f32 v[72:73], v[120:121], v[72:73]
	v_cvt_pk_bf16_f32 v70, v120, v92
	v_pk_add_f32 v[72:73], v[92:93], v[72:73]
	v_add3_u32 v92, s14, v186, v170
	v_pk_add_f32 v[72:73], v[122:123], v[72:73]
	v_cvt_pk_bf16_f32 v77, v80, v66
	v_pk_add_f32 v[72:73], v[94:95], v[72:73]
	v_cvt_pk_bf16_f32 v66, v121, v93
	v_add_f32_e32 v72, v72, v73
	v_add_u32_e32 v93, 0x2000, v92
	v_add_f32_e32 v175, v175, v72
	v_cvt_pk_bf16_f32 v76, v116, v64
	v_cvt_pk_bf16_f32 v72, v117, v65
	v_cvt_pk_bf16_f32 v73, v81, v67
	v_cvt_pk_bf16_f32 v78, v82, v68
	v_cvt_pk_bf16_f32 v74, v83, v69
	v_cvt_pk_bf16_f32 v75, v85, v71
	v_cvt_pk_bf16_f32 v68, v86, v88
	v_cvt_pk_bf16_f32 v64, v87, v89
	v_cvt_pk_bf16_f32 v69, v118, v90
	v_cvt_pk_bf16_f32 v65, v119, v91
	s_waitcnt lgkmcnt(0)
	v_mfma_f32_32x32x16_bf16 v[48:63], v[212:215], v[76:79], v[48:63]
	v_add_u32_e32 v92, 0x3000, v92
	v_cvt_pk_bf16_f32 v71, v122, v94
	v_cvt_pk_bf16_f32 v67, v123, v95
	v_mfma_f32_32x32x16_bf16 v[48:63], v[216:219], v[72:75], v[48:63]
	v_mfma_f32_32x32x16_bf16 v[32:47], v[220:223], v[76:79], v[32:47]
	v_mfma_f32_32x32x16_bf16 v[32:47], v[224:227], v[72:75], v[32:47]
	v_mfma_f32_32x32x16_bf16 v[48:63], v[228:231], v[68:71], v[48:63]
	v_mfma_f32_32x32x16_bf16 v[48:63], v[232:235], v[64:67], v[48:63]
	v_mfma_f32_32x32x16_bf16 v[32:47], v[236:239], v[68:71], v[32:47]
	v_mfma_f32_32x32x16_bf16 v[32:47], v[240:243], v[64:67], v[32:47]

; #define LAS __attribute__((address_space(3)))
; template <int BR>
; DI void attn_branch(const AttnCtx& c, unsigned long long tmask, const bf16_t* kbase, size_t kpitch, const bf16_t* vbase, size_t vpitch, f32x16 (&o)[2], float& lsum) {
;     ...
;             else interior = (jc * 64 + 63 <= c.tw) && (jc * 64 > c.tw + 31 - 512);
;             if (interior) {
;                 f32x16 s0, s1;
; #pragma unroll
;                 for (int i = 0; i < 16; ++i) { s0[i] = sbias; s1[i] = sbias; }
; #pragma unroll
;                 for (int st = 0; st < 4; ++st) {
;                     const bf16x8 kf0 = *(const LAS bf16x8*)(Ks + c.qi * 72 + 16 * st + 8 * c.hi), kf1 = *(const LAS bf16x8*)(Ks + (32 + c.qi) * 72 + 16 * st + 8 * c.hi);
;                     s0 = MFMA32(kf0, c.q[st], s0); s1 = MFMA32(kf1, c.q[st], s1);
;                 }
;                 float p0[16], p1[16];
; #pragma unroll
;                 for (int i = 0; i < 16; ++i) { p0[i] = __builtin_amdgcn_exp2f(s0[i]); p1[i] = __builtin_amdgcn_exp2f(s1[i]); }
;                 {
;                     float l0 = 0.f, l1 = 0.f;
; #pragma unroll
;                     for (int i = 0; i < 16; ++i) { l0 += p0[i]; l1 += p1[i]; }
;                     lsum += l0 + l1;
;                 }
;                 if (BR == 1) {
; #pragma unroll
;                     for (int gq = 0; gq < 4; ++gq) {
;                         const int jj = jc * 16 + gq * 2 + c.hi;
;                         __hip_atomic_fetch_add(c.impw + jj, (p0[4 * gq] + p0[4 * gq + 1]) + (p0[4 * gq + 2] + p0[4 * gq + 3]), __ATOMIC_RELAXED, __HIP_MEMORY_SCOPE_WORKGROUP);
;                         __hip_atomic_fetch_add(c.impw + jj + 1, p0[4 * gq + 3], __ATOMIC_RELAXED, __HIP_MEMORY_SCOPE_WORKGROUP);
;                     }
; #pragma unroll
;                     for (int gq = 0; gq < 4; ++gq) {
;                         const int jj = jc * 16 + 8 + gq * 2 + c.hi;
;                         __hip_atomic_fetch_add(c.impw + jj, (p1[4 * gq] + p1[4 * gq + 1]) + (p1[4 * gq + 2] + p1[4 * gq + 3]), __ATOMIC_RELAXED, __HIP_MEMORY_SCOPE_WORKGROUP);
;                         if (jj + 1 < 64) __hip_atomic_fetch_add(c.impw + jj + 1, p1[4 * gq + 3], __ATOMIC_RELAXED, __HIP_MEMORY_SCOPE_WORKGROUP);
;                     }
;                 }
;                 if (BR != 0) {
;                     unsigned pa[8], pb[8];
; #pragma unroll
.LBB0_403:
	v_lshlrev_b32_e32 v96, 1, v170
	v_add3_u32 v201, s11, v185, v96
	ds_read_b128 v[212:215], v201 offset:4608
	ds_read_b128 v[216:219], v201
	ds_read_b128 v[220:223], v201 offset:32
	ds_read_b128 v[224:227], v201 offset:4640
	ds_read_b128 v[228:231], v201 offset:64
	ds_read_b128 v[232:235], v201 offset:4672
	ds_read_b128 v[236:239], v201 offset:96
	ds_read_b128 v[240:243], v201 offset:4704
	s_waitcnt lgkmcnt(7)
	v_mfma_f32_32x32x16_bf16 v[112:127], v[212:215], v[130:133], 0
	s_waitcnt lgkmcnt(6)
	v_mfma_f32_32x32x16_bf16 v[96:111], v[216:219], v[130:133], 0
	s_waitcnt lgkmcnt(5)
	v_mfma_f32_32x32x16_bf16 v[96:111], v[220:223], v[134:137], v[96:111]
	s_waitcnt lgkmcnt(4)
	v_mfma_f32_32x32x16_bf16 v[112:127], v[224:227], v[134:137], v[112:127]
	s_waitcnt lgkmcnt(3)
	v_mfma_f32_32x32x16_bf16 v[96:111], v[228:231], v[138:141], v[96:111]
	s_waitcnt lgkmcnt(2)
	v_mfma_f32_32x32x16_bf16 v[112:127], v[232:235], v[138:141], v[112:127]
	s_waitcnt lgkmcnt(1)
	v_mfma_f32_32x32x16_bf16 v[96:111], v[236:239], v[142:145], v[96:111]
	s_waitcnt lgkmcnt(0)
	v_mfma_f32_32x32x16_bf16 v[112:127], v[240:243], v[142:145], v[112:127]
	v_add3_u32 v251, s11, v186, v170
	v_add_u32_e32 v255, 0x2000, v251
	v_add_u32_e32 v251, 0x3000, v251
	ds_read2_b64 v[212:215], v255 offset0:128 offset1:130
	ds_read2_b64 v[216:219], v255 offset0:136 offset1:138
	ds_read2_b64 v[220:223], v251 offset0:160 offset1:162
	ds_read2_b64 v[224:227], v251 offset0:168 offset1:170
	ds_read2_b64 v[228:231], v255 offset0:132 offset1:134
	ds_read2_b64 v[232:235], v255 offset0:140 offset1:142
	ds_read2_b64 v[236:239], v251 offset0:164 offset1:166
	ds_read2_b64 v[240:243], v251 offset0:172 offset1:174
	s_nop 9
	v_exp_f32_e32 v202, v96
	v_exp_f32_e32 v96, v97
	v_exp_f32_e32 v204, v106
	v_exp_f32_e32 v206, v108
	v_exp_f32_e32 v208, v110
	v_cvt_pk_bf16_f32 v108, v202, v96
	v_exp_f32_e32 v203, v112
	v_exp_f32_e32 v97, v113
	v_exp_f32_e32 v112, v98
	v_exp_f32_e32 v113, v114
	v_exp_f32_e32 v98, v99
	v_exp_f32_e32 v99, v115
	v_exp_f32_e32 v114, v100
	v_exp_f32_e32 v115, v116
	v_exp_f32_e32 v100, v101
	v_exp_f32_e32 v101, v117
	v_exp_f32_e32 v116, v102
	v_exp_f32_e32 v117, v118
	v_exp_f32_e32 v102, v103
	v_exp_f32_e32 v103, v119
	v_exp_f32_e32 v118, v104
	v_exp_f32_e32 v119, v120
	v_exp_f32_e32 v120, v105
	v_pk_add_f32 v[104:105], v[202:203], 0 op_sel_hi:[1,0]
	v_exp_f32_e32 v121, v121
	v_pk_add_f32 v[104:105], v[96:97], v[104:105]
	v_exp_f32_e32 v205, v122
	v_pk_add_f32 v[104:105], v[112:113], v[104:105]
	v_exp_f32_e32 v122, v107
	v_pk_add_f32 v[104:105], v[98:99], v[104:105]
	v_exp_f32_e32 v123, v123
	v_pk_add_f32 v[104:105], v[114:115], v[104:105]
	v_exp_f32_e32 v207, v124
	v_pk_add_f32 v[104:105], v[100:101], v[104:105]
	v_exp_f32_e32 v124, v109
	v_pk_add_f32 v[104:105], v[116:117], v[104:105]
	v_exp_f32_e32 v125, v125
	v_pk_add_f32 v[104:105], v[102:103], v[104:105]
	v_exp_f32_e32 v209, v126
	v_pk_add_f32 v[104:105], v[118:119], v[104:105]
	v_exp_f32_e32 v126, v111
	v_pk_add_f32 v[104:105], v[120:121], v[104:105]
	v_exp_f32_e32 v127, v127
	v_pk_add_f32 v[104:105], v[204:205], v[104:105]
	v_cvt_pk_bf16_f32 v111, v116, v102
	v_pk_add_f32 v[104:105], v[122:123], v[104:105]
	v_cvt_pk_bf16_f32 v102, v206, v124
	v_pk_add_f32 v[104:105], v[206:207], v[104:105]
	v_cvt_pk_bf16_f32 v109, v112, v98
	v_pk_add_f32 v[104:105], v[124:125], v[104:105]
	v_add3_u32 v124, s11, v186, v170
	v_pk_add_f32 v[104:105], v[208:209], v[104:105]
	v_cvt_pk_bf16_f32 v98, v207, v125
	v_pk_add_f32 v[104:105], v[126:127], v[104:105]
	v_add_u32_e32 v125, 0x2000, v124
	v_add_f32_e32 v104, v104, v105
	v_add_f32_e32 v174, v174, v104
	v_cvt_pk_bf16_f32 v104, v203, v97
	v_cvt_pk_bf16_f32 v105, v113, v99
	v_cvt_pk_bf16_f32 v110, v114, v100
	v_cvt_pk_bf16_f32 v106, v115, v101
	v_cvt_pk_bf16_f32 v107, v117, v103
	v_cvt_pk_bf16_f32 v100, v118, v120
	v_cvt_pk_bf16_f32 v96, v119, v121
	v_cvt_pk_bf16_f32 v101, v204, v122
	v_cvt_pk_bf16_f32 v97, v205, v123
	s_waitcnt lgkmcnt(0)
	v_mfma_f32_32x32x16_bf16 v[80:95], v[212:215], v[108:111], v[80:95]
	v_add_u32_e32 v124, 0x3000, v124
	v_cvt_pk_bf16_f32 v103, v208, v126
	v_cvt_pk_bf16_f32 v99, v209, v127
	v_mfma_f32_32x32x16_bf16 v[80:95], v[216:219], v[104:107], v[80:95]
	v_mfma_f32_32x32x16_bf16 v[64:79], v[220:223], v[108:111], v[64:79]
	v_mfma_f32_32x32x16_bf16 v[64:79], v[224:227], v[104:107], v[64:79]
	v_mfma_f32_32x32x16_bf16 v[80:95], v[228:231], v[100:103], v[80:95]
	v_mfma_f32_32x32x16_bf16 v[80:95], v[232:235], v[96:99], v[80:95]
	v_mfma_f32_32x32x16_bf16 v[64:79], v[236:239], v[100:103], v[64:79]
	v_mfma_f32_32x32x16_bf16 v[64:79], v[240:243], v[96:99], v[64:79]
	s_or_b64 exec, exec, s[0:1]
	s_andn2_b64 vcc, exec, s[4:5]
	s_xor_b64 s[2:3], s[2:3], -1
	s_cbranch_vccz .LBB0_306
